# P3b: odd XCDs run their sigmoid-gate tiles first and the gate-in-place tiles last (read-modify-write epilogues no longer coincide chip-wide)
# speedup vs baseline: 1.0425x; 1.0012x over previous
; DI int real_tile_row256(int tt) { return (tt >> 4) * L + NMETA + (tt & 15) * 256; }
; DI void phase3b(const Params& p, unsigned char* smem, int tid) {
;     ...
;     auto tile_ptrs = [&](int rb, const bf16_t*& P, const bf16_t*& Q) __attribute__((always_inline)) -> bool {
;         const int idp = rb + xcd * (per_round >> 3) + cu;
;         if (rb >= 16 * 64 || idp >= 16 * 64) return false;
;         const int half = idp >> 9, i9 = idp & 511, f = (i9 & 31) >> 2, tt = (i9 >> 5) * 4 + (i9 & 3);
;         P = (const bf16_t*)(ws + (half == 0 ? OFF_WZ : OFF_WG)) + (size_t)f * 256 * 1024;
;         Q = hb + (size_t)real_tile_row256(tt) * 1024;
;         return true;
;     };
;     GSets gs;
;     const bf16_t* Pn = nullptr; const bf16_t* Qn = nullptr;
;     bool vn = tile_ptrs(0, Pn, Qn);
;     if (vn) { int ti = tid; asm volatile("" : "+v"(ti)); gemm_issue(Pn, Qn, gs, ti); }
.LBB0_906:
	s_cmp_gt_i32 s62, 4
	s_cselect_b64 s[2:3], -1, 0
	s_cmp_lt_i32 s63, 4
	s_cselect_b64 s[4:5], -1, 0
	s_or_b64 s[2:3], s[2:3], s[4:5]
	s_and_b64 vcc, exec, s[2:3]
	s_cbranch_vccnz .LBB0_988
	s_mov_b32 s2, 0
	s_add_u32 s3, s56, 0x190fc00
	v_mbcnt_lo_u32_b32 v0, -1, s2
	v_mbcnt_hi_u32_b32 v0, -1, v0
	v_or_b32_e32 v198, s65, v0
	s_load_dword s2, s[0:1], 0x80
	s_addc_u32 s16, s57, 0
	s_and_b32 s6, s64, 7
	s_lshr_b32 s7, s64, 3
	s_add_u32 s4, s0, 0x80
	s_addc_u32 s5, s1, 0
	s_waitcnt lgkmcnt(0)
	s_ashr_i32 s8, s2, 3
	s_mul_i32 s17, s8, s6
	s_add_i32 s17, s17, s7
	s_cmpk_lt_i32 s17, 0x400
	s_mov_b64 s[6:7], 0
	s_cselect_b64 s[20:21], -1, 0
	s_cmpk_gt_i32 s17, 0x3ff
	s_mov_b64 s[8:9], 0
	s_cbranch_scc1 .LBB0_909
	s_lshr_b32 s8, s17, 3
	s_and_b32 s6, s8, 60
	s_and_b32 s7, s17, 3
	s_or_b32 s9, s6, s7
	s_lshl_b32 s98, s64, 9
	s_and_b32 s98, s98, 0x200
	s_xor_b32 s98, s98, s17
	s_cmpk_lt_u32 s98, 0x200
	s_mov_b32 s6, 0x9cfc00
	s_cselect_b32 s6, s6, 0xdcfc00
	s_add_u32 s6, s56, s6
	s_addc_u32 s7, s57, 0
	s_lshl_b32 s10, s17, 17
	s_and_b32 s10, s10, 0x380000
	s_add_u32 s6, s6, s10
	s_addc_u32 s7, s7, 0
	s_bfe_u32 s8, s8, 0x20004
	s_lshl_b32 s9, s9, 8
	s_mulk_i32 s8, 0x1010
	s_and_b32 s9, s9, 0xf00
	s_add_i32 s8, s8, s9
	s_lshl_b32 s8, s8, 11
	s_add_i32 s8, s8, 0x8000
	s_add_u32 s8, s3, s8
	s_addc_u32 s9, s16, 0

; DI int real_tile_row256(int tt) { return (tt >> 4) * L + NMETA + (tt & 15) * 256; }
; DI void phase3b(const Params& p, unsigned char* smem, int tid) {
;     ...
;     auto tile_ptrs = [&](int rb, const bf16_t*& P, const bf16_t*& Q) __attribute__((always_inline)) -> bool {
;         const int idp = rb + xcd * (per_round >> 3) + cu;
;         if (rb >= 16 * 64 || idp >= 16 * 64) return false;
;         const int half = idp >> 9, i9 = idp & 511, f = (i9 & 31) >> 2, tt = (i9 >> 5) * 4 + (i9 & 3);
;         P = (const bf16_t*)(ws + (half == 0 ? OFF_WZ : OFF_WG)) + (size_t)f * 256 * 1024;
;         Q = hb + (size_t)real_tile_row256(tt) * 1024;
;         return true;
;     };
.LBB0_914:
	s_mov_b64 s[26:27], -1
	s_and_b64 vcc, exec, s[20:21]
	s_cbranch_vccnz .LBB0_919
	s_add_i32 s38, s14, s2
	s_add_i32 s26, s38, s17
	s_max_i32 s22, s38, s26
	s_cmpk_lt_i32 s22, 0x400
	s_cselect_b64 s[20:21], -1, 0
	s_cmpk_gt_i32 s22, 0x3ff
	s_mov_b64 s[22:23], s[6:7]
	s_mov_b64 s[24:25], s[8:9]
	s_cbranch_scc1 .LBB0_917
	s_lshr_b32 s24, s26, 3
	s_and_b32 s22, s24, 60
	s_and_b32 s23, s26, 3
	s_or_b32 s25, s22, s23
	s_lshl_b32 s98, s64, 9
	s_and_b32 s98, s98, 0x200
	s_xor_b32 s98, s98, s26
	s_cmpk_lt_u32 s98, 0x200
	s_cselect_b32 s22, s28, 0xdcfc00
	s_add_u32 s22, s56, s22
	s_addc_u32 s23, s57, 0
	s_lshl_b32 s26, s26, 17
	s_and_b32 s26, s26, 0x380000
	s_add_u32 s22, s22, s26
	s_addc_u32 s23, s23, 0
	s_bfe_u32 s24, s24, 0x20004
	s_lshl_b32 s25, s25, 8
	s_mulk_i32 s24, 0x1010
	s_and_b32 s25, s25, 0xf00
	s_add_i32 s24, s24, s25
	s_lshl_b32 s24, s24, 11
	s_add_i32 s24, s24, 0x8000
	s_add_u32 s24, s3, s24
	s_addc_u32 s25, s16, 0

; #define G_LOAD(pr, qr, kt_) if (MODE != 1) { _Pragma("unroll") for (int r = 0; r < NP; ++r) pr[r] = *(const u32x4*)(pp + (size_t)(r * 128) * ldp + (kt_) * BK); \
;                               _Pragma("unroll") for (int r = 0; r < NQ; ++r) qr[r] = *(const u32x4*)(qp + (size_t)(r * 128) * ldq + (kt_) * BK); }
; #define G_STORE(pr, qr, so_) { unsigned char* w_ = wP + (so_); \
;                               _Pragma("unroll") for (int r = 0; r < NP; ++r) *(u32x4*)(w_ + r * 128 * LROW) = pr[r]; \
;                               _Pragma("unroll") for (int r = 0; r < NQ; ++r) *(u32x4*)(w_ + BI * LROW + r * 128 * LROW) = qr[r]; }
; #define F_LOAD(fa, fb, so_, ks_) { _Pragma("unroll") for (int it = 0; it < WI; ++it) fa[it] = *(const bf16x8*)(rP + (so_) + it * 32 * LROW + (ks_) * 32); \
;                                   _Pragma("unroll") for (int jt = 0; jt < 2; ++jt) fb[jt] = *(const bf16x8*)(rQ + (so_) + jt * 32 * LROW + (ks_) * 32); }
; #define G_LOAD(pr, qr, kt_) if (MODE != 1) { _Pragma("unroll") for (int r = 0; r < NP; ++r) pr[r] = *(const u32x4*)(pp + (size_t)(r * 128) * ldp + (kt_) * BK); \
;                               _Pragma("unroll") for (int r = 0; r < NQ; ++r) qr[r] = *(const u32x4*)(qp + (size_t)(r * 128) * ldq + (kt_) * BK); }
; #define G_STORE(pr, qr, so_) { unsigned char* w_ = wP + (so_); \
;                               _Pragma("unroll") for (int r = 0; r < NP; ++r) *(u32x4*)(w_ + r * 128 * LROW) = pr[r]; \
;                               _Pragma("unroll") for (int r = 0; r < NQ; ++r) *(u32x4*)(w_ + BI * LROW + r * 128 * LROW) = qr[r]; }
; #define F_LOAD(fa, fb, so_, ks_) { _Pragma("unroll") for (int it = 0; it < WI; ++it) fa[it] = *(const bf16x8*)(rP + (so_) + it * 32 * LROW + (ks_) * 32); \
;                                   _Pragma("unroll") for (int jt = 0; jt < 2; ++jt) fb[jt] = *(const bf16x8*)(rQ + (so_) + jt * 32 * LROW + (ks_) * 32); }
;     ...
;     G_STORE(p0, q0, 0)
;     G_LOAD(p0, q0, 3)
;     G_STORE(p1, q1, STAGE)
;     __syncthreads();
;     F_LOAD(fa0, fb0, 0, 0)
;     int cur = 0, nxt = STAGE, wr = 2 * STAGE;
;     int kt = 0;
; #pragma unroll 1
;     for (; kt + 3 <= nk - 4; kt += 3) {
;         G_HALF(p1, q1, p2, q2, kt)
;         G_HALF(p2, q2, p0, q0, kt + 1)
;         G_HALF(p0, q0, p1, q1, kt + 2)
;     }
.LBB0_921:
	s_waitcnt lgkmcnt(1)
	s_nop 0
	v_mfma_f32_32x32x16_bf16 v[112:127], v[160:163], v[172:175], v[112:127]
	v_lshl_add_u64 v[228:229], v[190:191], 0, v[184:185]
	v_lshl_add_u64 v[230:231], v[196:197], 0, v[184:185]
	ds_read_b128 v[220:223], v201 offset:22560
	s_waitcnt vmcnt(7)
	ds_write_b128 v219, v[132:135]
	s_waitcnt lgkmcnt(2)
	v_mfma_f32_32x32x16_bf16 v[48:63], v[160:163], v[176:179], v[48:63]
	global_load_dwordx4 v[160:163], v[230:231], off offset:256
	ds_read_b128 v[132:135], v199 offset:2080
	v_mfma_f32_32x32x16_bf16 v[96:111], v[164:167], v[172:175], v[96:111]
	ds_read_b128 v[224:227], v201 offset:25120
	s_waitcnt vmcnt(7)
	ds_write_b128 v218, v[128:131]
	v_mfma_f32_32x32x16_bf16 v[32:47], v[164:167], v[176:179], v[32:47]
	v_add_co_u32_e32 v232, vcc, s29, v230
	ds_read_b128 v[128:131], v199 offset:4640
	s_nop 0
	v_addc_co_u32_e32 v233, vcc, 0, v231, vcc
	global_load_dwordx4 v[164:167], v[232:233], off offset:256
	v_mfma_f32_32x32x16_bf16 v[80:95], v[168:171], v[172:175], v[80:95]
	s_waitcnt vmcnt(7)
	ds_write_b128 v217, v[136:139]
	v_mfma_f32_32x32x16_bf16 v[16:31], v[168:171], v[176:179], v[16:31]
	global_load_dwordx4 v[168:171], v[228:229], off offset:256
	ds_read_b128 v[136:139], v199 offset:7200
	v_mfma_f32_32x32x16_bf16 v[64:79], v[180:183], v[172:175], v[64:79]
	s_waitcnt vmcnt(7)
	ds_write_b128 v216, v[140:143]
	v_mfma_f32_32x32x16_bf16 v[0:15], v[180:183], v[176:179], v[0:15]
	v_add_co_u32_e32 v234, vcc, s29, v228
	ds_read_b128 v[140:143], v199 offset:9760
	s_nop 0
	v_addc_co_u32_e32 v235, vcc, 0, v229, vcc
	global_load_dwordx4 v[172:175], v[234:235], off offset:256
	s_waitcnt lgkmcnt(7)
	v_mfma_f32_32x32x16_bf16 v[112:127], v[132:135], v[220:223], v[112:127]
	ds_read_b128 v[176:179], v201 offset:63488
	s_waitcnt lgkmcnt(7)
	v_mfma_f32_32x32x16_bf16 v[48:63], v[132:135], v[224:227], v[48:63]
	ds_read_b128 v[132:135], v199 offset:43008
	s_waitcnt lgkmcnt(6)
	v_mfma_f32_32x32x16_bf16 v[96:111], v[128:131], v[220:223], v[96:111]
	ds_read_b128 v[180:183], v200 offset:43520
	v_mfma_f32_32x32x16_bf16 v[32:47], v[128:131], v[224:227], v[32:47]
	ds_read_b128 v[128:131], v199 offset:45568
	s_waitcnt lgkmcnt(6)
	v_mfma_f32_32x32x16_bf16 v[80:95], v[136:139], v[220:223], v[80:95]
	v_mfma_f32_32x32x16_bf16 v[16:31], v[136:139], v[224:227], v[16:31]
	ds_read_b128 v[136:139], v199 offset:48128
	s_waitcnt lgkmcnt(5)
	v_mfma_f32_32x32x16_bf16 v[64:79], v[140:143], v[220:223], v[64:79]
	v_mfma_f32_32x32x16_bf16 v[0:15], v[140:143], v[224:227], v[0:15]
	ds_read_b128 v[140:143], v199 offset:50688
	s_waitcnt lgkmcnt(0)
	s_barrier
	v_mfma_f32_32x32x16_bf16 v[112:127], v[132:135], v[176:179], v[112:127]
	ds_read_b128 v[220:223], v201 offset:63520
	s_waitcnt vmcnt(7)
	ds_write_b128 v202, v[144:147] offset:2048
	v_mfma_f32_32x32x16_bf16 v[48:63], v[132:135], v[180:183], v[48:63]
	global_load_dwordx4 v[132:135], v[230:231], off offset:320
	ds_read_b128 v[144:147], v199 offset:43040
	v_mfma_f32_32x32x16_bf16 v[96:111], v[128:131], v[176:179], v[96:111]
	ds_read_b128 v[224:227], v200 offset:43552
	s_waitcnt vmcnt(7)
	ds_write_b128 v202, v[152:155] offset:12288
	v_mfma_f32_32x32x16_bf16 v[32:47], v[128:131], v[180:183], v[32:47]
	global_load_dwordx4 v[128:131], v[232:233], off offset:320
	ds_read_b128 v[152:155], v199 offset:45600
	v_mfma_f32_32x32x16_bf16 v[80:95], v[136:139], v[176:179], v[80:95]
	s_waitcnt vmcnt(7)
	ds_write_b128 v202, v[148:151] offset:22528
	v_mfma_f32_32x32x16_bf16 v[16:31], v[136:139], v[180:183], v[16:31]
	global_load_dwordx4 v[136:139], v[228:229], off offset:320
	ds_read_b128 v[148:151], v199 offset:48160
	v_mfma_f32_32x32x16_bf16 v[64:79], v[140:143], v[176:179], v[64:79]
	s_waitcnt vmcnt(7)
	ds_write_b128 v202, v[156:159] offset:32768
	v_mfma_f32_32x32x16_bf16 v[0:15], v[140:143], v[180:183], v[0:15]
	global_load_dwordx4 v[140:143], v[234:235], off offset:320
	ds_read_b128 v[156:159], v199 offset:50720
	s_waitcnt lgkmcnt(7)
	v_mfma_f32_32x32x16_bf16 v[112:127], v[144:147], v[220:223], v[112:127]
	ds_read_b128 v[176:179], v215
	s_waitcnt lgkmcnt(7)
	v_mfma_f32_32x32x16_bf16 v[48:63], v[144:147], v[224:227], v[48:63]
	ds_read_b128 v[144:147], v214
	s_waitcnt lgkmcnt(6)
	v_mfma_f32_32x32x16_bf16 v[96:111], v[152:155], v[220:223], v[96:111]
	ds_read_b128 v[180:183], v213
	v_mfma_f32_32x32x16_bf16 v[32:47], v[152:155], v[224:227], v[32:47]
	ds_read_b128 v[152:155], v212
	s_waitcnt lgkmcnt(6)
	v_mfma_f32_32x32x16_bf16 v[80:95], v[148:151], v[220:223], v[80:95]
	v_mfma_f32_32x32x16_bf16 v[16:31], v[148:151], v[224:227], v[16:31]
	ds_read_b128 v[148:151], v211
	s_waitcnt lgkmcnt(5)
	v_mfma_f32_32x32x16_bf16 v[64:79], v[156:159], v[220:223], v[64:79]
	v_mfma_f32_32x32x16_bf16 v[0:15], v[156:159], v[224:227], v[0:15]
	ds_read_b128 v[156:159], v210
	s_waitcnt lgkmcnt(0)
	s_barrier
; #define G_HALF(pl, ql, ps, qs, kt_) { const int k4_ = min((kt_) + 4, nk - 1); \
;         SB G_LOAD(pl, ql, k4_) F_LOAD(fa1, fb1, cur, 1) SB G_MFMA(fa0, fb0) SB G_STORE(ps, qs, wr) F_LOAD(fa0, fb0, nxt, 0) SB G_MFMA(fa1, fb1) SB \
;         __syncthreads(); { const int t_ = cur; cur = nxt; nxt = wr; wr = t_; } }
; #define G_HALF(pl, ql, ps, qs, kt_) { const int k4_ = min((kt_) + 4, nk - 1); \
;         SB R_BURST1(fb0, fb1, cur, 1, pl, ql, k4_, ps, qs, wr) R_BURST2(fb1, fb0, nxt, 0, ps, qs, wr) \
;         __syncthreads(); { const int t_ = cur; cur = nxt; nxt = wr; wr = t_; } }
; #define G_HALF(pl, ql, ps, qs, kt_) { const int k4_ = min((kt_) + 4, nk - 1); \
;         SB R_BURST1(fb0, fb1, cur, 1, pl, ql, k4_, ps, qs, wr) R_BURST2(fb1, fb0, nxt, 0, ps, qs, wr) \
;         __syncthreads(); { const int t_ = cur; cur = nxt; nxt = wr; wr = t_; } }
; #define G_HALF_NL(ps, qs, kt_) { SB R_BURST1S(fb0, fb1, cur, 1, ps, qs, wr) R_BURST2(fb1, fb0, nxt, 0, ps, qs, wr) \
;         __syncthreads(); { const int t_ = cur; cur = nxt; nxt = wr; wr = t_; } }
;     ...
;     for (; kt + 3 <= nk - 4; kt += 3) {
;         G_HALF(p1, q1, p2, q2, kt)
;         G_HALF(p2, q2, p0, q0, kt + 1)
;         G_HALF(p0, q0, p1, q1, kt + 2)
;     }
;     G_HALF(p1, q1, p2, q2, nk - 5)
;     G_HALF_NL(p0, q0, nk - 4)
;     G_HALF_NL(p1, q1, nk - 3)
	v_mfma_f32_32x32x16_bf16 v[112:127], v[144:147], v[176:179], v[112:127]
	ds_read_b128 v[220:223], v209
	s_waitcnt vmcnt(7)
	ds_write_b128 v202, v[160:163] offset:43008
	v_mfma_f32_32x32x16_bf16 v[48:63], v[144:147], v[180:183], v[48:63]
	global_load_dwordx4 v[144:147], v[230:231], off offset:384
	ds_read_b128 v[160:163], v208
	v_mfma_f32_32x32x16_bf16 v[96:111], v[152:155], v[176:179], v[96:111]
	ds_read_b128 v[224:227], v207
	s_waitcnt vmcnt(7)
	ds_write_b128 v202, v[164:167] offset:53248
	v_mfma_f32_32x32x16_bf16 v[32:47], v[152:155], v[180:183], v[32:47]
	global_load_dwordx4 v[152:155], v[232:233], off offset:384
	ds_read_b128 v[164:167], v206
	v_mfma_f32_32x32x16_bf16 v[80:95], v[148:151], v[176:179], v[80:95]
	s_waitcnt vmcnt(7)
	ds_write_b128 v202, v[168:171] offset:63488
	v_mfma_f32_32x32x16_bf16 v[16:31], v[148:151], v[180:183], v[16:31]
	global_load_dwordx4 v[148:151], v[228:229], off offset:384
	ds_read_b128 v[168:171], v205
	v_mfma_f32_32x32x16_bf16 v[64:79], v[156:159], v[176:179], v[64:79]
	s_waitcnt vmcnt(7)
	ds_write_b128 v203, v[172:175]
	v_mfma_f32_32x32x16_bf16 v[0:15], v[156:159], v[180:183], v[0:15]
	global_load_dwordx4 v[156:159], v[234:235], off offset:384
	ds_read_b128 v[180:183], v204
	s_waitcnt lgkmcnt(7)
	v_mfma_f32_32x32x16_bf16 v[112:127], v[160:163], v[220:223], v[112:127]
	ds_read_b128 v[172:175], v201 offset:22528
	s_waitcnt lgkmcnt(7)
	v_mfma_f32_32x32x16_bf16 v[48:63], v[160:163], v[224:227], v[48:63]
	ds_read_b128 v[160:163], v199 offset:2048
	s_waitcnt lgkmcnt(6)
	v_mfma_f32_32x32x16_bf16 v[96:111], v[164:167], v[220:223], v[96:111]
	ds_read_b128 v[176:179], v201 offset:25088
	v_mfma_f32_32x32x16_bf16 v[32:47], v[164:167], v[224:227], v[32:47]
	ds_read_b128 v[164:167], v199 offset:4608
	s_waitcnt lgkmcnt(6)
	v_mfma_f32_32x32x16_bf16 v[80:95], v[168:171], v[220:223], v[80:95]
	v_mfma_f32_32x32x16_bf16 v[16:31], v[168:171], v[224:227], v[16:31]
	ds_read_b128 v[168:171], v199 offset:7168
	s_waitcnt lgkmcnt(5)
	v_mfma_f32_32x32x16_bf16 v[64:79], v[180:183], v[220:223], v[64:79]
	v_mfma_f32_32x32x16_bf16 v[0:15], v[180:183], v[224:227], v[0:15]
	ds_read_b128 v[180:183], v199 offset:9728
	s_add_i32 s20, s20, 3
	v_lshl_add_u64 v[196:197], v[196:197], 0, s[18:19]
	s_cmp_lt_u32 s20, 26
	v_lshl_add_u64 v[190:191], v[190:191], 0, s[18:19]
	s_waitcnt lgkmcnt(0)
	s_barrier
	s_cbranch_scc1 .LBB0_921
	v_mfma_f32_32x32x16_bf16 v[112:127], v[160:163], v[172:175], v[112:127]
	ds_read_b128 v[220:223], v201 offset:22560
	s_waitcnt vmcnt(7)
	ds_write_b128 v219, v[132:135]
	v_mfma_f32_32x32x16_bf16 v[48:63], v[160:163], v[176:179], v[48:63]
	global_load_dwordx4 v[160:163], v[194:195], off offset:1984
	ds_read_b128 v[194:197], v199 offset:2080
	v_mfma_f32_32x32x16_bf16 v[96:111], v[164:167], v[172:175], v[96:111]
	ds_read_b128 v[224:227], v201 offset:25120
	s_waitcnt vmcnt(7)
	ds_write_b128 v218, v[128:131]
	v_mfma_f32_32x32x16_bf16 v[32:47], v[164:167], v[176:179], v[32:47]
	global_load_dwordx4 v[164:167], v[192:193], off offset:1984
	ds_read_b128 v[190:193], v199 offset:4640
	v_mfma_f32_32x32x16_bf16 v[80:95], v[168:171], v[172:175], v[80:95]
	s_waitcnt vmcnt(7)
	ds_write_b128 v217, v[136:139]
	v_mfma_f32_32x32x16_bf16 v[16:31], v[168:171], v[176:179], v[16:31]
	global_load_dwordx4 v[168:171], v[188:189], off offset:1984
	ds_read_b128 v[228:231], v199 offset:7200
	v_mfma_f32_32x32x16_bf16 v[64:79], v[180:183], v[172:175], v[64:79]
	s_waitcnt vmcnt(7)
	ds_write_b128 v216, v[140:143]
	v_mfma_f32_32x32x16_bf16 v[0:15], v[180:183], v[176:179], v[0:15]
	global_load_dwordx4 v[172:175], v[186:187], off offset:1984
	ds_read_b128 v[176:179], v199 offset:9760
	s_waitcnt lgkmcnt(7)
	v_mfma_f32_32x32x16_bf16 v[112:127], v[194:197], v[220:223], v[112:127]
	ds_read_b128 v[180:183], v201 offset:63488
	s_waitcnt lgkmcnt(7)
	v_mfma_f32_32x32x16_bf16 v[48:63], v[194:197], v[224:227], v[48:63]
	ds_read_b128 v[186:189], v199 offset:43008
	s_waitcnt lgkmcnt(6)
	v_mfma_f32_32x32x16_bf16 v[96:111], v[190:193], v[220:223], v[96:111]
	ds_read_b128 v[194:197], v200 offset:43520
	v_mfma_f32_32x32x16_bf16 v[32:47], v[190:193], v[224:227], v[32:47]
	ds_read_b128 v[190:193], v199 offset:45568
	s_waitcnt lgkmcnt(6)
	v_mfma_f32_32x32x16_bf16 v[80:95], v[228:231], v[220:223], v[80:95]
	v_mfma_f32_32x32x16_bf16 v[16:31], v[228:231], v[224:227], v[16:31]
	ds_read_b128 v[216:219], v199 offset:48128
	s_waitcnt lgkmcnt(5)
	v_mfma_f32_32x32x16_bf16 v[64:79], v[176:179], v[220:223], v[64:79]
	v_mfma_f32_32x32x16_bf16 v[0:15], v[176:179], v[224:227], v[0:15]
	ds_read_b128 v[176:179], v199 offset:50688
	s_waitcnt lgkmcnt(0)
	s_barrier
	v_mfma_f32_32x32x16_bf16 v[112:127], v[186:189], v[180:183], v[112:127]
	ds_read_b128 v[220:223], v201 offset:63520
	s_waitcnt vmcnt(7)
	ds_write_b128 v202, v[144:147] offset:2048
	v_mfma_f32_32x32x16_bf16 v[48:63], v[186:189], v[194:197], v[48:63]
	ds_read_b128 v[186:189], v199 offset:43040
	v_mfma_f32_32x32x16_bf16 v[96:111], v[190:193], v[180:183], v[96:111]
	ds_read_b128 v[224:227], v200 offset:43552
	s_waitcnt vmcnt(6)
	ds_write_b128 v202, v[152:155] offset:12288
	v_mfma_f32_32x32x16_bf16 v[32:47], v[190:193], v[194:197], v[32:47]
	ds_read_b128 v[190:193], v199 offset:45600
	v_mfma_f32_32x32x16_bf16 v[80:95], v[216:219], v[180:183], v[80:95]
	s_waitcnt vmcnt(5)
	ds_write_b128 v202, v[148:151] offset:22528
	v_mfma_f32_32x32x16_bf16 v[16:31], v[216:219], v[194:197], v[16:31]
	ds_read_b128 v[216:219], v199 offset:48160
	v_mfma_f32_32x32x16_bf16 v[64:79], v[176:179], v[180:183], v[64:79]
	s_waitcnt vmcnt(4)
	ds_write_b128 v202, v[156:159] offset:32768
	v_mfma_f32_32x32x16_bf16 v[0:15], v[176:179], v[194:197], v[0:15]
	ds_read_b128 v[176:179], v199 offset:50720
	s_waitcnt lgkmcnt(7)
	v_mfma_f32_32x32x16_bf16 v[112:127], v[186:189], v[220:223], v[112:127]
	ds_read_b128 v[180:183], v215
	s_waitcnt lgkmcnt(7)
	v_mfma_f32_32x32x16_bf16 v[48:63], v[186:189], v[224:227], v[48:63]
	ds_read_b128 v[186:189], v214
	s_waitcnt lgkmcnt(6)
	v_mfma_f32_32x32x16_bf16 v[96:111], v[190:193], v[220:223], v[96:111]
	ds_read_b128 v[194:197], v213
	v_mfma_f32_32x32x16_bf16 v[32:47], v[190:193], v[224:227], v[32:47]
	ds_read_b128 v[190:193], v212
	s_waitcnt lgkmcnt(6)
	v_mfma_f32_32x32x16_bf16 v[80:95], v[216:219], v[220:223], v[80:95]
	v_mfma_f32_32x32x16_bf16 v[16:31], v[216:219], v[224:227], v[16:31]
	ds_read_b128 v[212:215], v211
	s_waitcnt lgkmcnt(5)
	v_mfma_f32_32x32x16_bf16 v[64:79], v[176:179], v[220:223], v[64:79]
	v_mfma_f32_32x32x16_bf16 v[0:15], v[176:179], v[224:227], v[0:15]
	ds_read_b128 v[176:179], v210
	s_waitcnt lgkmcnt(0)
	s_barrier
; #define G_HALF(pl, ql, ps, qs, kt_) { const int k4_ = min((kt_) + 4, nk - 1); \
;         SB G_LOAD(pl, ql, k4_) F_LOAD(fa1, fb1, cur, 1) SB G_MFMA(fa0, fb0) SB G_STORE(ps, qs, wr) F_LOAD(fa0, fb0, nxt, 0) SB G_MFMA(fa1, fb1) SB \
;         __syncthreads(); { const int t_ = cur; cur = nxt; nxt = wr; wr = t_; } }
; #define G_HALF(pl, ql, ps, qs, kt_) { const int k4_ = min((kt_) + 4, nk - 1); \
;         SB R_BURST1(fb0, fb1, cur, 1, pl, ql, k4_, ps, qs, wr) R_BURST2(fb1, fb0, nxt, 0, ps, qs, wr) \
;         __syncthreads(); { const int t_ = cur; cur = nxt; nxt = wr; wr = t_; } }
;     ...
;     G_HALF(p1, q1, p2, q2, nk - 5)
;     G_HALF_NL(p0, q0, nk - 4)
;     G_HALF_NL(p1, q1, nk - 3)
;     G_HALF_NN(nk - 2)
;     G_HALF_NN(nk - 1)
; DI void phase3b(const Params& p, unsigned char* smem, int tid) {
;     ...
;     auto tile_ptrs = [&](int rb, const bf16_t*& P, const bf16_t*& Q) __attribute__((always_inline)) -> bool {
;         const int idp = rb + xcd * (per_round >> 3) + cu;
;         if (rb >= 16 * 64 || idp >= 16 * 64) return false;
;         const int half = idp >> 9, i9 = idp & 511, f = (i9 & 31) >> 2, tt = (i9 >> 5) * 4 + (i9 & 3);
;         P = (const bf16_t*)(ws + (half == 0 ? OFF_WZ : OFF_WG)) + (size_t)f * 256 * 1024;
;         Q = hb + (size_t)real_tile_row256(tt) * 1024;
;         return true;
;     };
;     GSets gs;
;     const bf16_t* Pn = nullptr; const bf16_t* Qn = nullptr;
;     bool vn = tile_ptrs(0, Pn, Qn);
;     if (vn) { int ti = tid; asm volatile("" : "+v"(ti)); gemm_issue(Pn, Qn, gs, ti); }
;     for (int rb = 0; rb < 16 * 64; rb += per_round) {
;         const int idp = rb + xcd * (per_round >> 3) + cu;
;         const bool v = vn;
;         const bf16_t* P = Pn; const bf16_t* Q = Qn;
;         if (!v) { vn = tile_ptrs(rb + per_round, Pn, Qn); if (vn) { int ti = tid; asm volatile("" : "+v"(ti)); gemm_issue(Pn, Qn, gs, ti); } continue; }
;         const int half = idp >> 9, i9 = idp & 511;
;         const int f = (i9 & 31) >> 2, tt = (i9 >> 5) * 4 + (i9 & 3);
;         const int r0 = real_tile_row256(tt);
;         f32x16 acc[4][2];
;         { int tl = tid; asm volatile("" : "+v"(tl));
;           gemm_tile3p<4, 4>(P, 1024, Q, 1024, lds, acc, tl, gs); }
;         vn = tile_ptrs(rb + per_round, Pn, Qn);
;         if (vn) { int ti = tid; asm volatile("" : "+v"(ti)); gemm_issue(Pn, Qn, gs, ti); }
	v_mfma_f32_32x32x16_bf16 v[112:127], v[186:189], v[180:183], v[112:127]
	ds_read_b128 v[216:219], v209
	s_waitcnt vmcnt(3)
	ds_write_b128 v202, v[160:163] offset:43008
	v_mfma_f32_32x32x16_bf16 v[48:63], v[186:189], v[194:197], v[48:63]
	ds_read_b128 v[186:189], v208
	v_mfma_f32_32x32x16_bf16 v[96:111], v[190:193], v[180:183], v[96:111]
	ds_read_b128 v[208:211], v207
	s_waitcnt vmcnt(2)
	ds_write_b128 v202, v[164:167] offset:53248
	v_mfma_f32_32x32x16_bf16 v[32:47], v[190:193], v[194:197], v[32:47]
	ds_read_b128 v[190:193], v206
	v_mfma_f32_32x32x16_bf16 v[80:95], v[212:215], v[180:183], v[80:95]
	s_waitcnt vmcnt(1)
	ds_write_b128 v202, v[168:171] offset:63488
	v_mfma_f32_32x32x16_bf16 v[16:31], v[212:215], v[194:197], v[16:31]
	ds_read_b128 v[212:215], v205
	v_mfma_f32_32x32x16_bf16 v[64:79], v[176:179], v[180:183], v[64:79]
	s_waitcnt vmcnt(0)
	ds_write_b128 v203, v[172:175]
	v_mfma_f32_32x32x16_bf16 v[0:15], v[176:179], v[194:197], v[0:15]
	ds_read_b128 v[176:179], v204
	s_waitcnt lgkmcnt(7)
	v_mfma_f32_32x32x16_bf16 v[112:127], v[186:189], v[216:219], v[112:127]
	ds_read_b128 v[180:183], v201 offset:22528
	s_waitcnt lgkmcnt(7)
	v_mfma_f32_32x32x16_bf16 v[48:63], v[186:189], v[208:211], v[48:63]
	ds_read_b128 v[186:189], v199 offset:2048
	s_waitcnt lgkmcnt(6)
	v_mfma_f32_32x32x16_bf16 v[96:111], v[190:193], v[216:219], v[96:111]
	ds_read_b128 v[194:197], v201 offset:25088
	v_mfma_f32_32x32x16_bf16 v[32:47], v[190:193], v[208:211], v[32:47]
	ds_read_b128 v[190:193], v199 offset:4608
	s_waitcnt lgkmcnt(6)
	v_mfma_f32_32x32x16_bf16 v[80:95], v[212:215], v[216:219], v[80:95]
	v_mfma_f32_32x32x16_bf16 v[16:31], v[212:215], v[208:211], v[16:31]
	ds_read_b128 v[202:205], v199 offset:7168
	s_waitcnt lgkmcnt(5)
	v_mfma_f32_32x32x16_bf16 v[64:79], v[176:179], v[216:219], v[64:79]
	v_mfma_f32_32x32x16_bf16 v[0:15], v[176:179], v[208:211], v[0:15]
	ds_read_b128 v[176:179], v199 offset:9728
	s_waitcnt lgkmcnt(0)
	s_barrier
	v_mfma_f32_32x32x16_bf16 v[112:127], v[186:189], v[180:183], v[112:127]
	ds_read_b128 v[206:209], v201 offset:22560
	v_mfma_f32_32x32x16_bf16 v[48:63], v[186:189], v[194:197], v[48:63]
	ds_read_b128 v[186:189], v199 offset:2080
	v_mfma_f32_32x32x16_bf16 v[96:111], v[190:193], v[180:183], v[96:111]
	ds_read_b128 v[210:213], v201 offset:25120
	v_mfma_f32_32x32x16_bf16 v[32:47], v[190:193], v[194:197], v[32:47]
	ds_read_b128 v[190:193], v199 offset:4640
	v_mfma_f32_32x32x16_bf16 v[80:95], v[202:205], v[180:183], v[80:95]
	v_mfma_f32_32x32x16_bf16 v[16:31], v[202:205], v[194:197], v[16:31]
	ds_read_b128 v[202:205], v199 offset:7200
	v_mfma_f32_32x32x16_bf16 v[64:79], v[176:179], v[180:183], v[64:79]
	v_mfma_f32_32x32x16_bf16 v[0:15], v[176:179], v[194:197], v[0:15]
	ds_read_b128 v[176:179], v199 offset:9760
	s_waitcnt lgkmcnt(4)
	v_mfma_f32_32x32x16_bf16 v[112:127], v[186:189], v[206:209], v[112:127]
	ds_read_b128 v[180:183], v201 offset:63488
	s_waitcnt lgkmcnt(4)
	v_mfma_f32_32x32x16_bf16 v[48:63], v[186:189], v[210:213], v[48:63]
	ds_read_b128 v[186:189], v199 offset:43008
	s_waitcnt lgkmcnt(4)
	v_mfma_f32_32x32x16_bf16 v[96:111], v[190:193], v[206:209], v[96:111]
	ds_read_b128 v[194:197], v200 offset:43520
	v_mfma_f32_32x32x16_bf16 v[32:47], v[190:193], v[210:213], v[32:47]
	ds_read_b128 v[190:193], v199 offset:45568
	s_waitcnt lgkmcnt(5)
	v_mfma_f32_32x32x16_bf16 v[80:95], v[202:205], v[206:209], v[80:95]
	v_mfma_f32_32x32x16_bf16 v[16:31], v[202:205], v[210:213], v[16:31]
	ds_read_b128 v[202:205], v199 offset:48128
	s_waitcnt lgkmcnt(5)
	v_mfma_f32_32x32x16_bf16 v[64:79], v[176:179], v[206:209], v[64:79]
	v_mfma_f32_32x32x16_bf16 v[0:15], v[176:179], v[210:213], v[0:15]
	ds_read_b128 v[176:179], v199 offset:50688
	s_waitcnt lgkmcnt(0)
	s_barrier
	v_mfma_f32_32x32x16_bf16 v[112:127], v[186:189], v[180:183], v[112:127]
	ds_read_b128 v[206:209], v201 offset:63520
	v_mfma_f32_32x32x16_bf16 v[48:63], v[186:189], v[194:197], v[48:63]
	ds_read_b128 v[186:189], v199 offset:43040
	v_mfma_f32_32x32x16_bf16 v[96:111], v[190:193], v[180:183], v[96:111]
	ds_read_b128 v[210:213], v200 offset:43552
	v_mfma_f32_32x32x16_bf16 v[32:47], v[190:193], v[194:197], v[32:47]
	ds_read_b128 v[190:193], v199 offset:45600
	v_mfma_f32_32x32x16_bf16 v[80:95], v[202:205], v[180:183], v[80:95]
	v_mfma_f32_32x32x16_bf16 v[16:31], v[202:205], v[194:197], v[16:31]
	ds_read_b128 v[200:203], v199 offset:48160
	v_mfma_f32_32x32x16_bf16 v[64:79], v[176:179], v[180:183], v[64:79]
	v_mfma_f32_32x32x16_bf16 v[0:15], v[176:179], v[194:197], v[0:15]
	ds_read_b128 v[176:179], v199 offset:50720
	s_waitcnt lgkmcnt(4)
	v_mfma_f32_32x32x16_bf16 v[112:127], v[186:189], v[206:209], v[112:127]
	s_waitcnt lgkmcnt(3)
	v_mfma_f32_32x32x16_bf16 v[48:63], v[186:189], v[210:213], v[48:63]
	s_waitcnt lgkmcnt(2)
	v_mfma_f32_32x32x16_bf16 v[96:111], v[190:193], v[206:209], v[96:111]
	v_mfma_f32_32x32x16_bf16 v[32:47], v[190:193], v[210:213], v[32:47]
	s_waitcnt lgkmcnt(1)
	v_mfma_f32_32x32x16_bf16 v[80:95], v[200:203], v[206:209], v[80:95]
	v_mfma_f32_32x32x16_bf16 v[16:31], v[200:203], v[210:213], v[16:31]
	s_waitcnt lgkmcnt(0)
	v_mfma_f32_32x32x16_bf16 v[64:79], v[176:179], v[206:209], v[64:79]
	v_mfma_f32_32x32x16_bf16 v[0:15], v[176:179], v[210:213], v[0:15]
	s_add_i32 s38, s14, s2
	s_add_i32 s22, s38, s17
	s_max_i32 s23, s38, s22
	s_cmpk_lt_i32 s23, 0x400
	s_cselect_b64 s[20:21], -1, 0
	s_cmpk_gt_i32 s23, 0x3ff
	s_barrier
	s_cbranch_scc1 .LBB0_924
	s_lshr_b32 s8, s22, 3
	s_and_b32 s6, s8, 60
	s_and_b32 s7, s22, 3
	s_or_b32 s9, s6, s7
	s_lshl_b32 s98, s64, 9
	s_and_b32 s98, s98, 0x200
	s_xor_b32 s98, s98, s22
	s_cmpk_lt_u32 s98, 0x200
	s_cselect_b32 s6, s28, 0xdcfc00
	s_add_u32 s6, s56, s6
	s_addc_u32 s7, s57, 0
	s_lshl_b32 s22, s22, 17
	s_and_b32 s22, s22, 0x380000
	s_add_u32 s6, s6, s22
	s_addc_u32 s7, s7, 0
	s_bfe_u32 s8, s8, 0x20004
	s_lshl_b32 s9, s9, 8
	s_mulk_i32 s8, 0x1010
	s_and_b32 s9, s9, 0xf00
	s_add_i32 s8, s8, s9
	s_lshl_b32 s8, s8, 11
	s_add_i32 s8, s8, 0x8000
	s_add_u32 s8, s3, s8
	s_addc_u32 s9, s16, 0

; DI unsigned pk2(float lo, float hi) { f32x2 v = {lo, hi}; bf2_t b = __builtin_convertvector(v, bf2_t); return __builtin_bit_cast(unsigned, b); }
; DI u32x2 pk4(float a, float b, float c, float d) { u32x2 r; r.x = pk2(a, b); r.y = pk2(c, d); return r; }
; DI float bf_lo(unsigned u) { return __uint_as_float(u << 16); }
; DI float bf_hi(unsigned u) { return __uint_as_float(u & 0xffff0000u); }
; DI float fsigmoid(float z) { return __builtin_amdgcn_rcpf(1.0f + __expf(-z)); }
; DI float fsilu(float z) { return z * fsigmoid(z); }
; DI void phase3b(const Params& p, unsigned char* smem, int tid) {
;     ...
;         int te = tid; asm volatile("" : "+v"(te));
;         const int lane = te & 63, wid = te >> 6, wj = wid & 3, ln = lane & 31;
;         float rsj[2];
; #pragma unroll
;         for (int jt = 0; jt < 2; ++jt) rsj[jt] = rstd[r0 + wj * 64 + jt * 32 + ln];
;         if (half == 0) {
;             bf16_t* obuf = (bf16_t*)(ws + (f < 4 ? OFF_QN : OFF_FQ)) + (f & 3) * 256;
;             staged_rows_rmw<4, 4>(lds, te,
;                 [&](int it, int jt, int g) { const float sc = rsj[jt];
;                     return pk4(fsilu(acc[it][jt][4 * g] * sc), fsilu(acc[it][jt][4 * g + 1] * sc), fsilu(acc[it][jt][4 * g + 2] * sc), fsilu(acc[it][jt][4 * g + 3] * sc)); },
;                 [&](int row, int col) { return *(const u32x4*)(obuf + (size_t)(r0 + row) * 1024 + col); },
;                 [&](int row, int col, u32x4 v, u32x4 o) { u32x4 w;
; #pragma unroll
;                     for (int e = 0; e < 4; ++e) w[e] = pk2(bf_lo(o[e]) * bf_lo(v[e]), bf_hi(o[e]) * bf_hi(v[e]));
;                     *(u32x4*)(obuf + (size_t)(r0 + row) * 1024 + col) = w; });
;         } else {
;             unsigned char* gt = ws + OFF_G + ((size_t)(f * 64 + tt) * 8 + wid) * 16384 + lane * 16;
; #pragma unroll
;             for (int it = 0; it < 4; ++it)
; #pragma unroll
;                 for (int jt = 0; jt < 2; ++jt)
; #pragma unroll
;                     for (int gp = 0; gp < 2; ++gp) {
;                         const float sc = rsj[jt];
;                         u32x4 w;
; #pragma unroll
;                         for (int e = 0; e < 4; ++e) w[e] = pk2(fsigmoid(acc[it][jt][8 * gp + 2 * e] * sc), fsigmoid(acc[it][jt][8 * gp + 2 * e + 1] * sc));
;                         __builtin_nontemporal_store(w, (u32x4*)(gt + ((it * 2 + jt) * 2 + gp) * 1024));
;                     }
;         }
.LBB0_926:
	s_add_i32 s24, s14, s17
	s_lshr_b32 s22, s24, 3
	s_and_b32 s14, s22, 60
	s_and_b32 s23, s24, 3
	s_or_b32 s14, s14, s23
	s_bfe_u32 s22, s22, 0x20004
	s_lshl_b32 s23, s14, 8
	s_mulk_i32 s22, 0x1010
	s_and_b32 s23, s23, 0xf00
	s_add_i32 s26, s22, s23
	v_mov_b32_e32 v177, v198
	s_add_i32 s26, s26, 16
	s_bfe_u32 s25, s24, 0x30002
	v_and_b32_e32 v179, 31, v177
	v_and_b32_e32 v176, 0xc0, v177
	v_add3_u32 v184, v176, s26, v179
	v_lshl_add_u64 v[180:181], v[184:185], 2, s[10:11]
	global_load_dword v178, v[180:181], off
	global_load_dword v176, v[180:181], off offset:128
	v_ashrrev_i32_e32 v180, 6, v177
	s_mov_b64 s[22:23], -1
	s_lshl_b32 s98, s64, 9
	s_and_b32 s98, s98, 0x200
	s_xor_b32 s98, s98, s24
	s_cmpk_gt_u32 s98, 0x1ff
	v_ashrrev_i32_e32 v181, 31, v180
	s_cbranch_scc0 .LBB0_928
	s_waitcnt vmcnt(1)
	v_mul_f32_e32 v186, v112, v178
	v_mul_f32_e32 v187, v113, v178
	s_lshl_b32 s22, s25, 9
	s_lshl_b32 s14, s14, 3
	v_mul_f32_e32 v186, 0xbfb8aa3b, v186
	v_mul_f32_e32 v187, 0xbfb8aa3b, v187
	s_or_b32 s14, s14, s22
	v_exp_f32_e32 v186, v186
	v_exp_f32_e32 v187, v187
	v_lshl_add_u64 v[182:183], v[180:181], 0, s[14:15]
	v_lshlrev_b64 v[182:183], 14, v[182:183]
	v_lshlrev_b32_e32 v184, 4, v177
	v_lshl_add_u64 v[182:183], s[12:13], 0, v[182:183]
	v_and_b32_e32 v184, 0x3f0, v184
	v_lshl_add_u64 v[182:183], v[182:183], 0, v[184:185]
	v_add_f32_e32 v184, 1.0, v186
	v_add_f32_e32 v186, 1.0, v187
	v_mul_f32_e32 v187, v114, v178
	v_mul_f32_e32 v188, v115, v178
	v_mul_f32_e32 v189, v116, v178
	v_mul_f32_e32 v190, v117, v178
	v_mul_f32_e32 v187, 0xbfb8aa3b, v187
	v_mul_f32_e32 v188, 0xbfb8aa3b, v188
	v_mul_f32_e32 v189, 0xbfb8aa3b, v189
	v_mul_f32_e32 v190, 0xbfb8aa3b, v190
	v_exp_f32_e32 v187, v187
	v_exp_f32_e32 v188, v188
	v_exp_f32_e32 v189, v189
	v_exp_f32_e32 v190, v190
	v_mul_f32_e32 v191, v118, v178
	v_mul_f32_e32 v192, v119, v178
	v_add_f32_e32 v187, 1.0, v187
	v_add_f32_e32 v188, 1.0, v188
	v_add_f32_e32 v189, 1.0, v189
	v_add_f32_e32 v190, 1.0, v190
	v_mul_f32_e32 v191, 0xbfb8aa3b, v191
	v_mul_f32_e32 v192, 0xbfb8aa3b, v192
	v_rcp_f32_e32 v187, v187
	v_rcp_f32_e32 v188, v188
	v_rcp_f32_e32 v189, v189
	v_exp_f32_e32 v191, v191
	v_exp_f32_e32 v192, v192
	v_rcp_f32_e32 v190, v190
	v_cvt_pk_bf16_f32 v187, v187, v188
	v_add_f32_e32 v191, 1.0, v191
	v_add_f32_e32 v192, 1.0, v192
	v_cvt_pk_bf16_f32 v188, v189, v190
	v_mul_f32_e32 v190, v121, v178
	v_rcp_f32_e32 v184, v184
	v_rcp_f32_e32 v186, v186
	v_rcp_f32_e32 v191, v191
	v_rcp_f32_e32 v192, v192
	v_mul_f32_e32 v190, 0xbfb8aa3b, v190
	v_exp_f32_e32 v190, v190
	v_cvt_pk_bf16_f32 v186, v184, v186
	v_cvt_pk_bf16_f32 v189, v191, v192
	global_store_dwordx4 v[182:183], v[186:189], off nt
	v_mul_f32_e32 v184, v120, v178
	v_mul_f32_e32 v191, v126, v178
	v_add_f32_e32 v186, 1.0, v190
	v_mul_f32_e32 v187, v122, v178
	v_mul_f32_e32 v188, v123, v178
	v_mul_f32_e32 v189, v124, v178
	v_mul_f32_e32 v190, v125, v178
	v_mul_f32_e32 v187, 0xbfb8aa3b, v187
	v_mul_f32_e32 v188, 0xbfb8aa3b, v188
	v_mul_f32_e32 v189, 0xbfb8aa3b, v189
	v_mul_f32_e32 v190, 0xbfb8aa3b, v190
	v_exp_f32_e32 v187, v187
	v_exp_f32_e32 v188, v188
	v_exp_f32_e32 v189, v189
	v_exp_f32_e32 v190, v190
	v_mul_f32_e32 v192, v127, v178
	v_mul_f32_e32 v184, 0xbfb8aa3b, v184
	v_add_f32_e32 v187, 1.0, v187
	v_add_f32_e32 v188, 1.0, v188
	v_add_f32_e32 v189, 1.0, v189
	v_add_f32_e32 v190, 1.0, v190
	v_mul_f32_e32 v191, 0xbfb8aa3b, v191
	v_mul_f32_e32 v192, 0xbfb8aa3b, v192
	v_exp_f32_e32 v184, v184
	v_rcp_f32_e32 v187, v187
	v_rcp_f32_e32 v188, v188
	v_rcp_f32_e32 v189, v189
	v_exp_f32_e32 v191, v191
	v_exp_f32_e32 v192, v192
	v_rcp_f32_e32 v190, v190
	v_add_f32_e32 v184, 1.0, v184
	v_add_f32_e32 v191, 1.0, v191
	v_add_f32_e32 v192, 1.0, v192
	v_cvt_pk_bf16_f32 v187, v187, v188
	v_cvt_pk_bf16_f32 v188, v189, v190
	s_waitcnt vmcnt(1)
	v_mul_f32_e32 v190, v49, v176
	v_rcp_f32_e32 v184, v184
	v_rcp_f32_e32 v186, v186
	v_rcp_f32_e32 v191, v191
	v_rcp_f32_e32 v192, v192
	v_mul_f32_e32 v190, 0xbfb8aa3b, v190
	v_exp_f32_e32 v190, v190
	v_cvt_pk_bf16_f32 v186, v184, v186
	v_cvt_pk_bf16_f32 v189, v191, v192
	global_store_dwordx4 v[182:183], v[186:189], off offset:1024 nt
	v_mul_f32_e32 v184, v48, v176
	v_mul_f32_e32 v191, v54, v176
	v_add_f32_e32 v186, 1.0, v190
	v_mul_f32_e32 v187, v50, v176
	v_mul_f32_e32 v188, v51, v176
	v_mul_f32_e32 v189, v52, v176
	v_mul_f32_e32 v190, v53, v176
	v_mul_f32_e32 v187, 0xbfb8aa3b, v187
	v_mul_f32_e32 v188, 0xbfb8aa3b, v188
	v_mul_f32_e32 v189, 0xbfb8aa3b, v189
	v_mul_f32_e32 v190, 0xbfb8aa3b, v190
	v_exp_f32_e32 v187, v187
	v_exp_f32_e32 v188, v188
	v_exp_f32_e32 v189, v189
	v_exp_f32_e32 v190, v190
	v_mul_f32_e32 v192, v55, v176
	v_mul_f32_e32 v184, 0xbfb8aa3b, v184
	v_add_f32_e32 v187, 1.0, v187
	v_add_f32_e32 v188, 1.0, v188
	v_add_f32_e32 v189, 1.0, v189
	v_add_f32_e32 v190, 1.0, v190
	v_mul_f32_e32 v191, 0xbfb8aa3b, v191
	v_mul_f32_e32 v192, 0xbfb8aa3b, v192
	v_exp_f32_e32 v184, v184
	v_rcp_f32_e32 v187, v187
	v_rcp_f32_e32 v188, v188
	v_rcp_f32_e32 v189, v189
	v_exp_f32_e32 v191, v191
	v_exp_f32_e32 v192, v192
	v_rcp_f32_e32 v190, v190
	v_add_f32_e32 v184, 1.0, v184
	v_add_f32_e32 v191, 1.0, v191
	v_add_f32_e32 v192, 1.0, v192
	v_cvt_pk_bf16_f32 v187, v187, v188
	v_cvt_pk_bf16_f32 v188, v189, v190
	v_mul_f32_e32 v190, v57, v176
	v_rcp_f32_e32 v184, v184
	v_rcp_f32_e32 v186, v186
	v_rcp_f32_e32 v191, v191
	v_rcp_f32_e32 v192, v192
	v_mul_f32_e32 v190, 0xbfb8aa3b, v190
	v_exp_f32_e32 v190, v190
	v_cvt_pk_bf16_f32 v186, v184, v186
	v_cvt_pk_bf16_f32 v189, v191, v192
	global_store_dwordx4 v[182:183], v[186:189], off offset:2048 nt
	v_mul_f32_e32 v184, v56, v176
	v_mul_f32_e32 v191, v62, v176
	v_add_f32_e32 v186, 1.0, v190
; DI unsigned pk2(float lo, float hi) { f32x2 v = {lo, hi}; bf2_t b = __builtin_convertvector(v, bf2_t); return __builtin_bit_cast(unsigned, b); }
; DI float fsigmoid(float z) { return __builtin_amdgcn_rcpf(1.0f + __expf(-z)); }
; DI void phase3b(const Params& p, unsigned char* smem, int tid) {
;     ...
; #pragma unroll
;             for (int it = 0; it < 4; ++it)
; #pragma unroll
;                 for (int jt = 0; jt < 2; ++jt)
; #pragma unroll
;                     for (int gp = 0; gp < 2; ++gp) {
;                         const float sc = rsj[jt];
;                         u32x4 w;
; #pragma unroll
;                         for (int e = 0; e < 4; ++e) w[e] = pk2(fsigmoid(acc[it][jt][8 * gp + 2 * e] * sc), fsigmoid(acc[it][jt][8 * gp + 2 * e + 1] * sc));
;                         __builtin_nontemporal_store(w, (u32x4*)(gt + ((it * 2 + jt) * 2 + gp) * 1024));
;                     }
	v_mul_f32_e32 v187, v58, v176
	v_mul_f32_e32 v188, v59, v176
	v_mul_f32_e32 v189, v60, v176
	v_mul_f32_e32 v190, v61, v176
	v_mul_f32_e32 v187, 0xbfb8aa3b, v187
	v_mul_f32_e32 v188, 0xbfb8aa3b, v188
	v_mul_f32_e32 v189, 0xbfb8aa3b, v189
	v_mul_f32_e32 v190, 0xbfb8aa3b, v190
	v_exp_f32_e32 v187, v187
	v_exp_f32_e32 v188, v188
	v_exp_f32_e32 v189, v189
	v_exp_f32_e32 v190, v190
	v_mul_f32_e32 v192, v63, v176
	v_mul_f32_e32 v184, 0xbfb8aa3b, v184
	v_mul_f32_e32 v191, 0xbfb8aa3b, v191
	v_mul_f32_e32 v192, 0xbfb8aa3b, v192
	v_exp_f32_e32 v184, v184
	v_exp_f32_e32 v191, v191
	v_exp_f32_e32 v192, v192
	v_add_f32_e32 v187, 1.0, v187
	v_add_f32_e32 v188, 1.0, v188
	v_add_f32_e32 v189, 1.0, v189
	v_add_f32_e32 v190, 1.0, v190
	v_rcp_f32_e32 v187, v187
	v_rcp_f32_e32 v188, v188
	v_rcp_f32_e32 v189, v189
	v_rcp_f32_e32 v190, v190
	v_add_f32_e32 v184, 1.0, v184
	v_add_f32_e32 v191, 1.0, v191
	v_add_f32_e32 v192, 1.0, v192
	v_rcp_f32_e32 v184, v184
	v_rcp_f32_e32 v186, v186
	v_rcp_f32_e32 v191, v191
	v_rcp_f32_e32 v192, v192
	v_cvt_pk_bf16_f32 v187, v187, v188
	v_cvt_pk_bf16_f32 v188, v189, v190
	v_mul_f32_e32 v190, v97, v178
	v_mul_f32_e32 v190, 0xbfb8aa3b, v190
	v_exp_f32_e32 v190, v190
	v_cvt_pk_bf16_f32 v186, v184, v186
	v_cvt_pk_bf16_f32 v189, v191, v192
	global_store_dwordx4 v[182:183], v[186:189], off offset:3072 nt
	v_mul_f32_e32 v184, v96, v178
	v_mul_f32_e32 v184, 0xbfb8aa3b, v184
	v_mul_f32_e32 v188, v99, v178
	v_mul_f32_e32 v188, 0xbfb8aa3b, v188
	v_mul_f32_e32 v189, v100, v178
	v_add_f32_e32 v186, 1.0, v190
	v_exp_f32_e32 v188, v188
	v_mul_f32_e32 v189, 0xbfb8aa3b, v189
	v_mul_f32_e32 v190, v101, v178
	v_exp_f32_e32 v189, v189
	v_mul_f32_e32 v190, 0xbfb8aa3b, v190
	v_exp_f32_e32 v190, v190
	v_add_f32_e32 v188, 1.0, v188
	v_rcp_f32_e32 v191, v188
	v_add_f32_e32 v188, 1.0, v189
	v_mul_f32_e32 v189, v102, v178
	v_mul_f32_e32 v187, v98, v178
	v_rcp_f32_e32 v192, v188
	v_add_f32_e32 v188, 1.0, v190
	v_mul_f32_e32 v189, 0xbfb8aa3b, v189
	v_mul_f32_e32 v190, v103, v178
	v_mul_f32_e32 v187, 0xbfb8aa3b, v187
	v_exp_f32_e32 v189, v189
	v_mul_f32_e32 v190, 0xbfb8aa3b, v190
	v_exp_f32_e32 v187, v187
	v_exp_f32_e32 v190, v190
	v_rcp_f32_e32 v193, v188
	v_add_f32_e32 v188, 1.0, v189
	v_exp_f32_e32 v184, v184
	v_add_f32_e32 v187, 1.0, v187
	v_rcp_f32_e32 v194, v188
	v_add_f32_e32 v188, 1.0, v190
	v_rcp_f32_e32 v187, v187
	v_rcp_f32_e32 v195, v188
	v_add_f32_e32 v184, 1.0, v184
	v_rcp_f32_e32 v184, v184
	v_rcp_f32_e32 v186, v186
	v_cvt_pk_bf16_f32 v189, v187, v191
	v_cvt_pk_bf16_f32 v191, v194, v195
	v_mul_f32_e32 v194, v105, v178
	v_mul_f32_e32 v194, 0xbfb8aa3b, v194
	v_cvt_pk_bf16_f32 v190, v192, v193
	v_add_co_u32_e32 v192, vcc, s33, v182
	v_exp_f32_e32 v194, v194
	s_nop 0
	v_addc_co_u32_e32 v193, vcc, 0, v183, vcc
	v_cvt_pk_bf16_f32 v188, v184, v186
	v_add_co_u32_e32 v186, vcc, s34, v182
	v_mul_f32_e32 v184, v104, v178
	s_nop 0
	v_addc_co_u32_e32 v187, vcc, 0, v183, vcc
	global_store_dwordx4 v[186:187], v[188:191], off offset:-4096 nt
	v_mul_f32_e32 v195, v110, v178
	v_mul_f32_e32 v196, v111, v178
	v_add_f32_e32 v188, 1.0, v194
	v_mul_f32_e32 v189, v106, v178
	v_mul_f32_e32 v190, v107, v178
	v_mul_f32_e32 v191, v108, v178
	v_mul_f32_e32 v194, v109, v178
	v_mul_f32_e32 v189, 0xbfb8aa3b, v189
	v_mul_f32_e32 v190, 0xbfb8aa3b, v190
	v_mul_f32_e32 v191, 0xbfb8aa3b, v191
	v_mul_f32_e32 v194, 0xbfb8aa3b, v194
	v_exp_f32_e32 v189, v189
	v_exp_f32_e32 v190, v190
	v_exp_f32_e32 v191, v191
	v_exp_f32_e32 v194, v194
	v_mul_f32_e32 v184, 0xbfb8aa3b, v184
	v_add_f32_e32 v189, 1.0, v189
	v_add_f32_e32 v190, 1.0, v190
	v_add_f32_e32 v191, 1.0, v191
	v_add_f32_e32 v194, 1.0, v194
	v_mul_f32_e32 v195, 0xbfb8aa3b, v195
	v_mul_f32_e32 v196, 0xbfb8aa3b, v196
	v_exp_f32_e32 v184, v184
	v_rcp_f32_e32 v189, v189
	v_rcp_f32_e32 v190, v190
	v_rcp_f32_e32 v191, v191
	v_exp_f32_e32 v195, v195
	v_exp_f32_e32 v196, v196
	v_rcp_f32_e32 v194, v194
	v_add_f32_e32 v184, 1.0, v184
	v_add_f32_e32 v195, 1.0, v195
	v_add_f32_e32 v196, 1.0, v196
	v_cvt_pk_bf16_f32 v189, v189, v190
	v_cvt_pk_bf16_f32 v190, v191, v194
	v_mul_f32_e32 v194, v33, v176
	v_rcp_f32_e32 v184, v184
	v_rcp_f32_e32 v188, v188
	v_rcp_f32_e32 v195, v195
	v_rcp_f32_e32 v196, v196
	v_mul_f32_e32 v194, 0xbfb8aa3b, v194
	v_exp_f32_e32 v194, v194
	v_cvt_pk_bf16_f32 v188, v184, v188
	v_cvt_pk_bf16_f32 v191, v195, v196
	global_store_dwordx4 v[192:193], v[188:191], off offset:1024 nt
	v_mul_f32_e32 v184, v32, v176
	v_mul_f32_e32 v195, v38, v176
	v_add_f32_e32 v188, 1.0, v194
	v_mul_f32_e32 v189, v34, v176
	v_mul_f32_e32 v190, v35, v176
	v_mul_f32_e32 v191, v36, v176
	v_mul_f32_e32 v194, v37, v176
	v_mul_f32_e32 v189, 0xbfb8aa3b, v189
	v_mul_f32_e32 v190, 0xbfb8aa3b, v190
	v_mul_f32_e32 v191, 0xbfb8aa3b, v191
	v_mul_f32_e32 v194, 0xbfb8aa3b, v194
	v_exp_f32_e32 v189, v189
	v_exp_f32_e32 v190, v190
	v_exp_f32_e32 v191, v191
	v_exp_f32_e32 v194, v194
	v_mul_f32_e32 v196, v39, v176
	v_mul_f32_e32 v184, 0xbfb8aa3b, v184
	v_add_f32_e32 v189, 1.0, v189
	v_add_f32_e32 v190, 1.0, v190
	v_add_f32_e32 v191, 1.0, v191
	v_add_f32_e32 v194, 1.0, v194
	v_mul_f32_e32 v195, 0xbfb8aa3b, v195
	v_mul_f32_e32 v196, 0xbfb8aa3b, v196
	v_exp_f32_e32 v184, v184
	v_rcp_f32_e32 v189, v189
	v_rcp_f32_e32 v190, v190
	v_rcp_f32_e32 v191, v191
	v_exp_f32_e32 v195, v195
	v_exp_f32_e32 v196, v196
	v_rcp_f32_e32 v194, v194
	v_add_f32_e32 v184, 1.0, v184
	v_add_f32_e32 v195, 1.0, v195
	v_add_f32_e32 v196, 1.0, v196
	v_cvt_pk_bf16_f32 v189, v189, v190
	v_cvt_pk_bf16_f32 v190, v191, v194
	v_mul_f32_e32 v194, v41, v176
	v_rcp_f32_e32 v184, v184
	v_rcp_f32_e32 v188, v188
	v_rcp_f32_e32 v195, v195
	v_rcp_f32_e32 v196, v196
	v_mul_f32_e32 v194, 0xbfb8aa3b, v194
; DI unsigned pk2(float lo, float hi) { f32x2 v = {lo, hi}; bf2_t b = __builtin_convertvector(v, bf2_t); return __builtin_bit_cast(unsigned, b); }
; DI float fsigmoid(float z) { return __builtin_amdgcn_rcpf(1.0f + __expf(-z)); }
; DI void phase3b(const Params& p, unsigned char* smem, int tid) {
;     ...
; #pragma unroll
;             for (int it = 0; it < 4; ++it)
; #pragma unroll
;                 for (int jt = 0; jt < 2; ++jt)
; #pragma unroll
;                     for (int gp = 0; gp < 2; ++gp) {
;                         const float sc = rsj[jt];
;                         u32x4 w;
; #pragma unroll
;                         for (int e = 0; e < 4; ++e) w[e] = pk2(fsigmoid(acc[it][jt][8 * gp + 2 * e] * sc), fsigmoid(acc[it][jt][8 * gp + 2 * e + 1] * sc));
;                         __builtin_nontemporal_store(w, (u32x4*)(gt + ((it * 2 + jt) * 2 + gp) * 1024));
;                     }
	v_exp_f32_e32 v194, v194
	v_cvt_pk_bf16_f32 v188, v184, v188
	v_cvt_pk_bf16_f32 v191, v195, v196
	v_mul_f32_e32 v184, v40, v176
	global_store_dwordx4 v[192:193], v[188:191], off offset:2048 nt
	v_mul_f32_e32 v195, v46, v176
	v_mul_f32_e32 v196, v47, v176
	v_add_f32_e32 v188, 1.0, v194
	v_mul_f32_e32 v189, v42, v176
	v_mul_f32_e32 v190, v43, v176
	v_mul_f32_e32 v191, v44, v176
	v_mul_f32_e32 v194, v45, v176
	v_mul_f32_e32 v184, 0xbfb8aa3b, v184
	v_mul_f32_e32 v189, 0xbfb8aa3b, v189
	v_mul_f32_e32 v190, 0xbfb8aa3b, v190
	v_mul_f32_e32 v191, 0xbfb8aa3b, v191
	v_mul_f32_e32 v194, 0xbfb8aa3b, v194
	v_mul_f32_e32 v195, 0xbfb8aa3b, v195
	v_mul_f32_e32 v196, 0xbfb8aa3b, v196
	v_exp_f32_e32 v184, v184
	v_exp_f32_e32 v189, v189
	v_exp_f32_e32 v190, v190
	v_exp_f32_e32 v191, v191
	v_exp_f32_e32 v194, v194
	v_exp_f32_e32 v195, v195
	v_exp_f32_e32 v196, v196
	v_add_f32_e32 v184, 1.0, v184
	v_add_f32_e32 v189, 1.0, v189
	v_add_f32_e32 v190, 1.0, v190
	v_add_f32_e32 v191, 1.0, v191
	v_add_f32_e32 v194, 1.0, v194
	v_add_f32_e32 v195, 1.0, v195
	v_add_f32_e32 v196, 1.0, v196
	v_rcp_f32_e32 v184, v184
	v_rcp_f32_e32 v188, v188
	v_rcp_f32_e32 v189, v189
	v_rcp_f32_e32 v190, v190
	v_rcp_f32_e32 v191, v191
	v_rcp_f32_e32 v194, v194
	v_rcp_f32_e32 v195, v195
	v_rcp_f32_e32 v196, v196
	v_cvt_pk_bf16_f32 v188, v184, v188
	v_cvt_pk_bf16_f32 v189, v189, v190
	v_cvt_pk_bf16_f32 v190, v191, v194
	v_cvt_pk_bf16_f32 v191, v195, v196
	v_mul_f32_e32 v194, v81, v178
	v_mul_f32_e32 v194, 0xbfb8aa3b, v194
	global_store_dwordx4 v[192:193], v[188:191], off offset:3072 nt
	v_mul_f32_e32 v192, v85, v178
	v_exp_f32_e32 v194, v194
	v_mul_f32_e32 v189, v82, v178
	v_mul_f32_e32 v190, v83, v178
	v_mul_f32_e32 v191, v84, v178
	v_mul_f32_e32 v189, 0xbfb8aa3b, v189
	v_mul_f32_e32 v190, 0xbfb8aa3b, v190
	v_mul_f32_e32 v191, 0xbfb8aa3b, v191
	v_mul_f32_e32 v192, 0xbfb8aa3b, v192
	v_exp_f32_e32 v189, v189
	v_exp_f32_e32 v190, v190
	v_exp_f32_e32 v191, v191
	v_exp_f32_e32 v192, v192
	v_mul_f32_e32 v184, v80, v178
	v_add_f32_e32 v188, 1.0, v194
	v_mul_f32_e32 v193, v86, v178
	v_mul_f32_e32 v194, v87, v178
	v_mul_f32_e32 v184, 0xbfb8aa3b, v184
	v_add_f32_e32 v189, 1.0, v189
	v_add_f32_e32 v190, 1.0, v190
	v_add_f32_e32 v191, 1.0, v191
	v_add_f32_e32 v192, 1.0, v192
	v_mul_f32_e32 v193, 0xbfb8aa3b, v193
	v_mul_f32_e32 v194, 0xbfb8aa3b, v194
	v_exp_f32_e32 v184, v184
	v_rcp_f32_e32 v189, v189
	v_rcp_f32_e32 v190, v190
	v_rcp_f32_e32 v191, v191
	v_exp_f32_e32 v193, v193
	v_exp_f32_e32 v194, v194
	v_rcp_f32_e32 v192, v192
	v_add_f32_e32 v184, 1.0, v184
	v_add_f32_e32 v193, 1.0, v193
	v_add_f32_e32 v194, 1.0, v194
	v_cvt_pk_bf16_f32 v189, v189, v190
	v_cvt_pk_bf16_f32 v190, v191, v192
	v_mul_f32_e32 v192, v89, v178
	v_rcp_f32_e32 v184, v184
	v_rcp_f32_e32 v188, v188
	v_rcp_f32_e32 v193, v193
	v_rcp_f32_e32 v194, v194
	v_mul_f32_e32 v192, 0xbfb8aa3b, v192
	v_exp_f32_e32 v192, v192
	v_cvt_pk_bf16_f32 v188, v184, v188
	v_cvt_pk_bf16_f32 v191, v193, v194
	global_store_dwordx4 v[186:187], v[188:191], off nt
	v_mul_f32_e32 v184, v88, v178
	v_mul_f32_e32 v193, v94, v178
	v_add_f32_e32 v188, 1.0, v192
	v_mul_f32_e32 v189, v90, v178
	v_mul_f32_e32 v190, v91, v178
	v_mul_f32_e32 v191, v92, v178
	v_mul_f32_e32 v192, v93, v178
	v_mul_f32_e32 v189, 0xbfb8aa3b, v189
	v_mul_f32_e32 v190, 0xbfb8aa3b, v190
	v_mul_f32_e32 v191, 0xbfb8aa3b, v191
	v_mul_f32_e32 v192, 0xbfb8aa3b, v192
	v_exp_f32_e32 v189, v189
	v_exp_f32_e32 v190, v190
	v_exp_f32_e32 v191, v191
	v_exp_f32_e32 v192, v192
	v_mul_f32_e32 v194, v95, v178
	v_mul_f32_e32 v184, 0xbfb8aa3b, v184
	v_add_f32_e32 v189, 1.0, v189
	v_add_f32_e32 v190, 1.0, v190
	v_add_f32_e32 v191, 1.0, v191
	v_add_f32_e32 v192, 1.0, v192
	v_mul_f32_e32 v193, 0xbfb8aa3b, v193
	v_mul_f32_e32 v194, 0xbfb8aa3b, v194
	v_exp_f32_e32 v184, v184
	v_rcp_f32_e32 v189, v189
	v_rcp_f32_e32 v190, v190
	v_rcp_f32_e32 v191, v191
	v_exp_f32_e32 v193, v193
	v_exp_f32_e32 v194, v194
	v_rcp_f32_e32 v192, v192
	v_add_f32_e32 v184, 1.0, v184
	v_add_f32_e32 v193, 1.0, v193
	v_add_f32_e32 v194, 1.0, v194
	v_cvt_pk_bf16_f32 v189, v189, v190
	v_cvt_pk_bf16_f32 v190, v191, v192
	v_mul_f32_e32 v192, v17, v176
	v_rcp_f32_e32 v184, v184
	v_rcp_f32_e32 v188, v188
	v_rcp_f32_e32 v193, v193
	v_rcp_f32_e32 v194, v194
	v_mul_f32_e32 v192, 0xbfb8aa3b, v192
	v_exp_f32_e32 v192, v192
	v_cvt_pk_bf16_f32 v188, v184, v188
	v_cvt_pk_bf16_f32 v191, v193, v194
	global_store_dwordx4 v[186:187], v[188:191], off offset:1024 nt
	v_mul_f32_e32 v184, v16, v176
	v_mul_f32_e32 v193, v22, v176
	v_add_f32_e32 v188, 1.0, v192
	v_mul_f32_e32 v189, v18, v176
	v_mul_f32_e32 v190, v19, v176
	v_mul_f32_e32 v191, v20, v176
	v_mul_f32_e32 v192, v21, v176
	v_mul_f32_e32 v189, 0xbfb8aa3b, v189
	v_mul_f32_e32 v190, 0xbfb8aa3b, v190
	v_mul_f32_e32 v191, 0xbfb8aa3b, v191
	v_mul_f32_e32 v192, 0xbfb8aa3b, v192
	v_exp_f32_e32 v189, v189
	v_exp_f32_e32 v190, v190
	v_exp_f32_e32 v191, v191
	v_exp_f32_e32 v192, v192
	v_mul_f32_e32 v194, v23, v176
	v_mul_f32_e32 v184, 0xbfb8aa3b, v184
	v_add_f32_e32 v189, 1.0, v189
	v_add_f32_e32 v190, 1.0, v190
	v_add_f32_e32 v191, 1.0, v191
	v_add_f32_e32 v192, 1.0, v192
	v_mul_f32_e32 v193, 0xbfb8aa3b, v193
	v_mul_f32_e32 v194, 0xbfb8aa3b, v194
	v_exp_f32_e32 v184, v184
	v_rcp_f32_e32 v189, v189
	v_rcp_f32_e32 v190, v190
	v_rcp_f32_e32 v191, v191
	v_exp_f32_e32 v193, v193
	v_exp_f32_e32 v194, v194
	v_rcp_f32_e32 v192, v192
	v_add_f32_e32 v184, 1.0, v184
	v_add_f32_e32 v193, 1.0, v193
	v_add_f32_e32 v194, 1.0, v194
	v_cvt_pk_bf16_f32 v189, v189, v190
	v_cvt_pk_bf16_f32 v190, v191, v192
	v_mul_f32_e32 v192, v25, v176
	v_rcp_f32_e32 v184, v184
	v_rcp_f32_e32 v188, v188
	v_rcp_f32_e32 v193, v193
	v_rcp_f32_e32 v194, v194
; DI unsigned pk2(float lo, float hi) { f32x2 v = {lo, hi}; bf2_t b = __builtin_convertvector(v, bf2_t); return __builtin_bit_cast(unsigned, b); }
; DI float fsigmoid(float z) { return __builtin_amdgcn_rcpf(1.0f + __expf(-z)); }
; DI void phase3b(const Params& p, unsigned char* smem, int tid) {
;     ...
; #pragma unroll
;             for (int it = 0; it < 4; ++it)
; #pragma unroll
;                 for (int jt = 0; jt < 2; ++jt)
; #pragma unroll
;                     for (int gp = 0; gp < 2; ++gp) {
;                         const float sc = rsj[jt];
;                         u32x4 w;
; #pragma unroll
;                         for (int e = 0; e < 4; ++e) w[e] = pk2(fsigmoid(acc[it][jt][8 * gp + 2 * e] * sc), fsigmoid(acc[it][jt][8 * gp + 2 * e + 1] * sc));
;                         __builtin_nontemporal_store(w, (u32x4*)(gt + ((it * 2 + jt) * 2 + gp) * 1024));
;                     }
	v_mul_f32_e32 v192, 0xbfb8aa3b, v192
	v_exp_f32_e32 v192, v192
	v_cvt_pk_bf16_f32 v188, v184, v188
	v_cvt_pk_bf16_f32 v191, v193, v194
	v_mul_f32_e32 v184, v24, v176
	global_store_dwordx4 v[186:187], v[188:191], off offset:2048 nt
	v_mul_f32_e32 v193, v30, v176
	v_mul_f32_e32 v194, v31, v176
	v_add_f32_e32 v188, 1.0, v192
	v_mul_f32_e32 v189, v26, v176
	v_mul_f32_e32 v190, v27, v176
	v_mul_f32_e32 v191, v28, v176
	v_mul_f32_e32 v192, v29, v176
	v_mul_f32_e32 v184, 0xbfb8aa3b, v184
	v_mul_f32_e32 v189, 0xbfb8aa3b, v189
	v_mul_f32_e32 v190, 0xbfb8aa3b, v190
	v_mul_f32_e32 v191, 0xbfb8aa3b, v191
	v_mul_f32_e32 v192, 0xbfb8aa3b, v192
	v_mul_f32_e32 v193, 0xbfb8aa3b, v193
	v_mul_f32_e32 v194, 0xbfb8aa3b, v194
	v_exp_f32_e32 v184, v184
	v_exp_f32_e32 v189, v189
	v_exp_f32_e32 v190, v190
	v_exp_f32_e32 v191, v191
	v_exp_f32_e32 v192, v192
	v_exp_f32_e32 v193, v193
	v_exp_f32_e32 v194, v194
	v_add_f32_e32 v184, 1.0, v184
	v_add_f32_e32 v189, 1.0, v189
	v_add_f32_e32 v190, 1.0, v190
	v_add_f32_e32 v191, 1.0, v191
	v_add_f32_e32 v192, 1.0, v192
	v_add_f32_e32 v193, 1.0, v193
	v_add_f32_e32 v194, 1.0, v194
	v_rcp_f32_e32 v184, v184
	v_rcp_f32_e32 v188, v188
	v_rcp_f32_e32 v189, v189
	v_rcp_f32_e32 v190, v190
	v_rcp_f32_e32 v191, v191
	v_rcp_f32_e32 v192, v192
	v_rcp_f32_e32 v193, v193
	v_rcp_f32_e32 v194, v194
	v_cvt_pk_bf16_f32 v188, v184, v188
	v_cvt_pk_bf16_f32 v189, v189, v190
	v_cvt_pk_bf16_f32 v190, v191, v192
	v_cvt_pk_bf16_f32 v191, v193, v194
	v_mul_f32_e32 v192, v65, v178
	v_mul_f32_e32 v192, 0xbfb8aa3b, v192
	global_store_dwordx4 v[186:187], v[188:191], off offset:3072 nt
	v_mul_f32_e32 v187, v66, v178
	v_exp_f32_e32 v192, v192
	v_mul_f32_e32 v188, v67, v178
	v_mul_f32_e32 v189, v68, v178
	v_mul_f32_e32 v190, v69, v178
	v_mul_f32_e32 v187, 0xbfb8aa3b, v187
	v_mul_f32_e32 v188, 0xbfb8aa3b, v188
	v_mul_f32_e32 v189, 0xbfb8aa3b, v189
	v_mul_f32_e32 v190, 0xbfb8aa3b, v190
	v_exp_f32_e32 v187, v187
	v_exp_f32_e32 v188, v188
	v_exp_f32_e32 v189, v189
	v_exp_f32_e32 v190, v190
	v_mul_f32_e32 v184, v64, v178
	v_add_f32_e32 v186, 1.0, v192
	v_mul_f32_e32 v191, v70, v178
	v_mul_f32_e32 v192, v71, v178
	v_mul_f32_e32 v184, 0xbfb8aa3b, v184
	v_add_f32_e32 v187, 1.0, v187
	v_add_f32_e32 v188, 1.0, v188
	v_add_f32_e32 v189, 1.0, v189
	v_add_f32_e32 v190, 1.0, v190
	v_mul_f32_e32 v191, 0xbfb8aa3b, v191
	v_mul_f32_e32 v192, 0xbfb8aa3b, v192
	v_exp_f32_e32 v184, v184
	v_rcp_f32_e32 v187, v187
	v_rcp_f32_e32 v188, v188
	v_rcp_f32_e32 v189, v189
	v_exp_f32_e32 v191, v191
	v_exp_f32_e32 v192, v192
	v_rcp_f32_e32 v190, v190
	v_add_f32_e32 v184, 1.0, v184
	v_add_f32_e32 v191, 1.0, v191
	v_add_f32_e32 v192, 1.0, v192
	v_cvt_pk_bf16_f32 v187, v187, v188
	v_cvt_pk_bf16_f32 v188, v189, v190
	v_mul_f32_e32 v190, v73, v178
	v_rcp_f32_e32 v184, v184
	v_rcp_f32_e32 v186, v186
	v_rcp_f32_e32 v191, v191
	v_rcp_f32_e32 v192, v192
	v_mul_f32_e32 v190, 0xbfb8aa3b, v190
	v_exp_f32_e32 v190, v190
	v_add_co_u32_e32 v182, vcc, s35, v182
	v_cvt_pk_bf16_f32 v186, v184, v186
	v_cvt_pk_bf16_f32 v189, v191, v192
	v_addc_co_u32_e32 v183, vcc, 0, v183, vcc
	global_store_dwordx4 v[182:183], v[186:189], off nt
	v_mul_f32_e32 v184, v72, v178
	v_mul_f32_e32 v191, v78, v178
	v_add_f32_e32 v186, 1.0, v190
	v_mul_f32_e32 v187, v74, v178
	v_mul_f32_e32 v188, v75, v178
	v_mul_f32_e32 v189, v76, v178
	v_mul_f32_e32 v190, v77, v178
	v_mul_f32_e32 v187, 0xbfb8aa3b, v187
	v_mul_f32_e32 v188, 0xbfb8aa3b, v188
	v_mul_f32_e32 v189, 0xbfb8aa3b, v189
	v_mul_f32_e32 v190, 0xbfb8aa3b, v190
	v_exp_f32_e32 v187, v187
	v_exp_f32_e32 v188, v188
	v_exp_f32_e32 v189, v189
	v_exp_f32_e32 v190, v190
	v_mul_f32_e32 v192, v79, v178
	v_mul_f32_e32 v184, 0xbfb8aa3b, v184
; DI unsigned pk2(float lo, float hi) { f32x2 v = {lo, hi}; bf2_t b = __builtin_convertvector(v, bf2_t); return __builtin_bit_cast(unsigned, b); }
; DI float fsigmoid(float z) { return __builtin_amdgcn_rcpf(1.0f + __expf(-z)); }
; DI void phase3b(const Params& p, unsigned char* smem, int tid) {
;     ...
; #pragma unroll
;             for (int it = 0; it < 4; ++it)
; #pragma unroll
;                 for (int jt = 0; jt < 2; ++jt)
; #pragma unroll
;                     for (int gp = 0; gp < 2; ++gp) {
;                         const float sc = rsj[jt];
;                         u32x4 w;
; #pragma unroll
;                         for (int e = 0; e < 4; ++e) w[e] = pk2(fsigmoid(acc[it][jt][8 * gp + 2 * e] * sc), fsigmoid(acc[it][jt][8 * gp + 2 * e + 1] * sc));
;                         __builtin_nontemporal_store(w, (u32x4*)(gt + ((it * 2 + jt) * 2 + gp) * 1024));
;                     }
	v_add_f32_e32 v187, 1.0, v187
	v_add_f32_e32 v188, 1.0, v188
	v_add_f32_e32 v189, 1.0, v189
	v_add_f32_e32 v190, 1.0, v190
	v_mul_f32_e32 v191, 0xbfb8aa3b, v191
	v_mul_f32_e32 v192, 0xbfb8aa3b, v192
	v_exp_f32_e32 v184, v184
	v_rcp_f32_e32 v187, v187
	v_rcp_f32_e32 v188, v188
	v_rcp_f32_e32 v189, v189
	v_exp_f32_e32 v191, v191
	v_exp_f32_e32 v192, v192
	v_rcp_f32_e32 v190, v190
	v_add_f32_e32 v184, 1.0, v184
	v_add_f32_e32 v191, 1.0, v191
	v_add_f32_e32 v192, 1.0, v192
	v_cvt_pk_bf16_f32 v187, v187, v188
	v_cvt_pk_bf16_f32 v188, v189, v190
	v_mul_f32_e32 v190, v1, v176
	v_rcp_f32_e32 v184, v184
	v_rcp_f32_e32 v186, v186
	v_rcp_f32_e32 v191, v191
	v_rcp_f32_e32 v192, v192
	v_mul_f32_e32 v190, 0xbfb8aa3b, v190
	v_exp_f32_e32 v190, v190
	v_cvt_pk_bf16_f32 v186, v184, v186
	v_cvt_pk_bf16_f32 v189, v191, v192
	global_store_dwordx4 v[182:183], v[186:189], off offset:1024 nt
	v_mul_f32_e32 v184, v0, v176
	v_mul_f32_e32 v191, v6, v176
	v_add_f32_e32 v186, 1.0, v190
	v_mul_f32_e32 v187, v2, v176
	v_mul_f32_e32 v188, v3, v176
	v_mul_f32_e32 v189, v4, v176
	v_mul_f32_e32 v190, v5, v176
	v_mul_f32_e32 v187, 0xbfb8aa3b, v187
	v_mul_f32_e32 v188, 0xbfb8aa3b, v188
	v_mul_f32_e32 v189, 0xbfb8aa3b, v189
	v_mul_f32_e32 v190, 0xbfb8aa3b, v190
	v_exp_f32_e32 v187, v187
	v_exp_f32_e32 v188, v188
	v_exp_f32_e32 v189, v189
	v_exp_f32_e32 v190, v190
	v_mul_f32_e32 v192, v7, v176
	v_mul_f32_e32 v184, 0xbfb8aa3b, v184
	v_add_f32_e32 v187, 1.0, v187
	v_add_f32_e32 v188, 1.0, v188
	v_add_f32_e32 v189, 1.0, v189
	v_add_f32_e32 v190, 1.0, v190
	v_mul_f32_e32 v191, 0xbfb8aa3b, v191
	v_mul_f32_e32 v192, 0xbfb8aa3b, v192
	v_exp_f32_e32 v184, v184
	v_rcp_f32_e32 v187, v187
	v_rcp_f32_e32 v188, v188
	v_rcp_f32_e32 v189, v189
	v_exp_f32_e32 v191, v191
	v_exp_f32_e32 v192, v192
	v_rcp_f32_e32 v190, v190
	v_add_f32_e32 v184, 1.0, v184
	v_add_f32_e32 v191, 1.0, v191
	v_add_f32_e32 v192, 1.0, v192
	v_cvt_pk_bf16_f32 v187, v187, v188
	v_cvt_pk_bf16_f32 v188, v189, v190
	v_mul_f32_e32 v190, v9, v176
	v_rcp_f32_e32 v184, v184
	v_rcp_f32_e32 v186, v186
	v_rcp_f32_e32 v191, v191
	v_rcp_f32_e32 v192, v192
	v_mul_f32_e32 v190, 0xbfb8aa3b, v190
	v_exp_f32_e32 v190, v190
	v_cvt_pk_bf16_f32 v186, v184, v186
	v_cvt_pk_bf16_f32 v189, v191, v192
	v_mul_f32_e32 v184, v8, v176
	global_store_dwordx4 v[182:183], v[186:189], off offset:2048 nt
	v_mul_f32_e32 v191, v14, v176
	v_mul_f32_e32 v192, v15, v176
	v_add_f32_e32 v186, 1.0, v190
	v_mul_f32_e32 v187, v10, v176
	v_mul_f32_e32 v188, v11, v176
	v_mul_f32_e32 v189, v12, v176
	v_mul_f32_e32 v190, v13, v176
	v_mul_f32_e32 v184, 0xbfb8aa3b, v184
	v_mul_f32_e32 v187, 0xbfb8aa3b, v187
	v_mul_f32_e32 v188, 0xbfb8aa3b, v188
	v_mul_f32_e32 v189, 0xbfb8aa3b, v189
	v_mul_f32_e32 v190, 0xbfb8aa3b, v190
	v_mul_f32_e32 v191, 0xbfb8aa3b, v191
	v_mul_f32_e32 v192, 0xbfb8aa3b, v192
	v_exp_f32_e32 v184, v184
	v_exp_f32_e32 v187, v187
	v_exp_f32_e32 v188, v188
	v_exp_f32_e32 v189, v189
	v_exp_f32_e32 v190, v190
	v_exp_f32_e32 v191, v191
	v_exp_f32_e32 v192, v192
	v_add_f32_e32 v184, 1.0, v184
	v_add_f32_e32 v187, 1.0, v187
	v_add_f32_e32 v188, 1.0, v188
	v_add_f32_e32 v189, 1.0, v189
	v_add_f32_e32 v190, 1.0, v190
	v_add_f32_e32 v191, 1.0, v191
	v_add_f32_e32 v192, 1.0, v192
	v_rcp_f32_e32 v184, v184
	v_rcp_f32_e32 v186, v186
	v_rcp_f32_e32 v187, v187
	v_rcp_f32_e32 v188, v188
	v_rcp_f32_e32 v189, v189
	v_rcp_f32_e32 v190, v190
	v_rcp_f32_e32 v191, v191
	v_rcp_f32_e32 v192, v192
	v_cvt_pk_bf16_f32 v186, v184, v186
	v_cvt_pk_bf16_f32 v187, v187, v188
	v_cvt_pk_bf16_f32 v188, v189, v190
	v_cvt_pk_bf16_f32 v189, v191, v192
	global_store_dwordx4 v[182:183], v[186:189], off offset:3072 nt
	s_mov_b64 s[22:23], 0
